# v79 = v72 + select scoring with km rows through SGPRs, two-group rotating buffers: each s_load issued right after its buffer is consumed, next row prefetched during the current one (same FMA order)
# speedup vs baseline: 1.0100x; 1.0100x over previous
.LBB0_168:
	s_cmp_lt_u32 s20, 2
	s_cselect_b64 vcc, -1, 0
	s_add_i32 s35, s20, 1
	s_cmp_lg_u32 s20, 3
	s_cselect_b32 s6, s35, 3
	s_cmp_lt_u32 s6, 2
	s_cselect_b64 s[0:1], -1, 0
	v_cndmask_b32_e64 v0, v68, v196, s[0:1]
	s_and_b32 s0, s6, 1
	s_or_b32 s0, s0, s34
	s_lshl_b32 s0, s0, 6
	v_lshl_or_b32 v0, v0, 8, s0
	v_or3_b32 v0, v0, v189, s10
	v_mov_b32_e32 v1, s11
	v_lshlrev_b64 v[0:1], 7, v[0:1]
	v_lshl_add_u64 v[0:1], s[64:65], 0, v[0:1]
	global_load_dwordx4 v[28:31], v[0:1], off
	global_load_dwordx4 v[24:27], v[0:1], off offset:16
	global_load_dwordx4 v[20:23], v[0:1], off offset:32
	global_load_dwordx4 v[16:19], v[0:1], off offset:48
	global_load_dwordx4 v[12:15], v[0:1], off offset:64
	global_load_dwordx4 v[8:11], v[0:1], off offset:80
	global_load_dwordx4 v[4:7], v[0:1], off offset:96
	s_nop 0
	global_load_dwordx4 v[0:3], v[0:1], off offset:112
	v_cndmask_b32_e32 v75, v68, v196, vcc
	v_cmp_ne_u32_e32 vcc, 0, v75
	s_and_saveexec_b64 s[16:17], vcc
	s_cbranch_execz .LBB0_167
	s_waitcnt vmcnt(15)
	v_lshlrev_b32_e32 v76, 16, v60
	v_and_b32_e32 v60, 0xffff0000, v60
	v_lshlrev_b32_e32 v77, 16, v61
	v_and_b32_e32 v61, 0xffff0000, v61
	v_lshlrev_b32_e32 v78, 16, v62
	v_and_b32_e32 v62, 0xffff0000, v62
	v_lshlrev_b32_e32 v79, 16, v63
	v_and_b32_e32 v63, 0xffff0000, v63
	s_waitcnt vmcnt(14)
	v_lshlrev_b32_e32 v80, 16, v56
	v_and_b32_e32 v56, 0xffff0000, v56
	v_lshlrev_b32_e32 v81, 16, v57
	v_and_b32_e32 v57, 0xffff0000, v57
	v_lshlrev_b32_e32 v82, 16, v58
	v_and_b32_e32 v58, 0xffff0000, v58
	v_lshlrev_b32_e32 v83, 16, v59
	v_and_b32_e32 v59, 0xffff0000, v59
	s_waitcnt vmcnt(13)
	v_lshlrev_b32_e32 v84, 16, v52
	v_and_b32_e32 v52, 0xffff0000, v52
	v_lshlrev_b32_e32 v85, 16, v53
	v_and_b32_e32 v53, 0xffff0000, v53
	v_lshlrev_b32_e32 v86, 16, v54
	v_and_b32_e32 v54, 0xffff0000, v54
	v_lshlrev_b32_e32 v87, 16, v55
	v_and_b32_e32 v55, 0xffff0000, v55
	s_waitcnt vmcnt(12)
	v_lshlrev_b32_e32 v88, 16, v48
	v_and_b32_e32 v48, 0xffff0000, v48
	v_lshlrev_b32_e32 v89, 16, v49
	v_and_b32_e32 v49, 0xffff0000, v49
	v_lshlrev_b32_e32 v90, 16, v50
	v_and_b32_e32 v50, 0xffff0000, v50
	v_lshlrev_b32_e32 v91, 16, v51
	v_and_b32_e32 v51, 0xffff0000, v51
	s_waitcnt vmcnt(11)
	v_lshlrev_b32_e32 v92, 16, v44
	v_and_b32_e32 v93, 0xffff0000, v44
	v_lshlrev_b32_e32 v94, 16, v45
	v_and_b32_e32 v95, 0xffff0000, v45
	v_lshlrev_b32_e32 v96, 16, v46
	v_and_b32_e32 v46, 0xffff0000, v46
	v_lshlrev_b32_e32 v97, 16, v47
	v_and_b32_e32 v47, 0xffff0000, v47
	s_waitcnt vmcnt(10)
	v_lshlrev_b32_e32 v98, 16, v40
	v_and_b32_e32 v99, 0xffff0000, v40
	v_lshlrev_b32_e32 v100, 16, v41
	v_and_b32_e32 v101, 0xffff0000, v41
	v_lshlrev_b32_e32 v102, 16, v42
	v_and_b32_e32 v103, 0xffff0000, v42
	v_lshlrev_b32_e32 v104, 16, v43
	v_and_b32_e32 v105, 0xffff0000, v43
	s_waitcnt vmcnt(9)
	v_lshlrev_b32_e32 v106, 16, v36
	v_and_b32_e32 v107, 0xffff0000, v36
	v_lshlrev_b32_e32 v108, 16, v37
	v_and_b32_e32 v109, 0xffff0000, v37
	v_and_b32_e32 v37, 0xffff0000, v38
	v_lshlrev_b32_e32 v36, 16, v38
	v_and_b32_e32 v41, 0xffff0000, v39
	v_lshlrev_b32_e32 v40, 16, v39
	s_waitcnt vmcnt(8)
	v_and_b32_e32 v39, 0xffff0000, v32
	v_lshlrev_b32_e32 v38, 16, v32
	v_and_b32_e32 v43, 0xffff0000, v33
	v_lshlrev_b32_e32 v42, 16, v33
	v_and_b32_e32 v33, 0xffff0000, v34
	v_lshlrev_b32_e32 v32, 16, v34
	v_and_b32_e32 v45, 0xffff0000, v35
	v_lshlrev_b32_e32 v44, 16, v35
	v_mov_b32_e32 v35, -1
	s_mov_b32 s21, 0
	v_mov_b32_e32 v110, 0xff800000
	s_mov_b32 s22, 0
	s_mov_b64 s[0:1], 0
	v_mov_b32_e32 v111, 0xff800000
	v_mov_b32_e32 v34, -1
	v_mov_b32_e32 v112, -1
	v_mov_b32_e32 v113, 0xff800000
	s_load_dwordx8 s[44:51], s[28:29], 0x0
	s_load_dwordx8 s[76:83], s[28:29], 0x20
	s_load_dwordx8 s[92:99], s[28:29], 0x40
	s_load_dwordx4 s[52:55], s[28:29], 0x60
	s_load_dwordx4 s[84:87], s[28:29], 0x70
	s_branch .LBB0_173

.LBB0_173:
	s_add_u32 s30, s28, s22
	s_addc_u32 s31, s29, 0
	s_waitcnt lgkmcnt(0)
	v_fma_f32 v127, s44, v76, 0
	v_fmac_f32_e32 v127, s45, v60
	v_fmac_f32_e32 v127, s46, v77
	v_fmac_f32_e32 v127, s47, v61
	v_fmac_f32_e32 v127, s48, v78
	v_fmac_f32_e32 v127, s49, v62
	v_fmac_f32_e32 v127, s50, v79
	v_fmac_f32_e32 v127, s51, v63
	v_fmac_f32_e32 v127, s76, v80
	v_fmac_f32_e32 v127, s77, v56
	v_fmac_f32_e32 v127, s78, v81
	v_fmac_f32_e32 v127, s79, v57
	v_fmac_f32_e32 v127, s80, v82
	v_fmac_f32_e32 v127, s81, v58
	v_fmac_f32_e32 v127, s82, v83
	v_fmac_f32_e32 v127, s83, v59
	s_load_dwordx8 s[44:51], s[30:31], 0x80
	s_load_dwordx8 s[76:83], s[30:31], 0xa0
	v_fmac_f32_e32 v127, s92, v84
	v_fmac_f32_e32 v127, s93, v52
	v_fmac_f32_e32 v127, s94, v85
	v_fmac_f32_e32 v127, s95, v53
	v_fmac_f32_e32 v127, s96, v86
	v_fmac_f32_e32 v127, s97, v54
	v_fmac_f32_e32 v127, s98, v87
	v_fmac_f32_e32 v127, s99, v55
	v_fmac_f32_e32 v127, s52, v88
	v_fmac_f32_e32 v127, s53, v48
	v_fmac_f32_e32 v127, s54, v89
	v_fmac_f32_e32 v127, s55, v49
	v_fmac_f32_e32 v127, s84, v90
	v_fmac_f32_e32 v127, s85, v50
	v_fmac_f32_e32 v127, s86, v91
	v_fmac_f32_e32 v127, s87, v51
	s_waitcnt lgkmcnt(0)
	s_load_dwordx8 s[92:99], s[30:31], 0xc0
	s_load_dwordx4 s[52:55], s[30:31], 0xe0
	s_load_dwordx4 s[84:87], s[30:31], 0xf0
	v_fmac_f32_e32 v127, s44, v92
	v_fmac_f32_e32 v127, s45, v93
	v_fmac_f32_e32 v127, s46, v94
	v_fmac_f32_e32 v127, s47, v95
	v_fmac_f32_e32 v127, s48, v96
	v_fmac_f32_e32 v127, s49, v46
	v_fmac_f32_e32 v127, s50, v97
	v_fmac_f32_e32 v127, s51, v47
	v_fmac_f32_e32 v127, s76, v98
	v_fmac_f32_e32 v127, s77, v99
	v_fmac_f32_e32 v127, s78, v100
	v_fmac_f32_e32 v127, s79, v101
	v_fmac_f32_e32 v127, s80, v102
	v_fmac_f32_e32 v127, s81, v103
	v_fmac_f32_e32 v127, s82, v104
	v_fmac_f32_e32 v127, s83, v105
	s_waitcnt lgkmcnt(0)
	s_load_dwordx8 s[44:51], s[30:31], 0x100
	s_load_dwordx8 s[76:83], s[30:31], 0x120
	v_fmac_f32_e32 v127, s92, v106
	v_fmac_f32_e32 v127, s93, v107
	v_fmac_f32_e32 v127, s94, v108
	v_fmac_f32_e32 v127, s95, v109
	v_mul_f32_e32 v114, s96, v36
	v_mul_f32_e32 v115, s97, v37
	v_add_f32_e32 v114, v114, v127
	v_add_f32_e32 v122, v115, v114
	v_mul_f32_e32 v114, s98, v40
	v_mul_f32_e32 v115, s99, v41
	v_add_f32_e32 v114, v114, v122
	v_add_f32_e32 v122, v115, v114
	v_mul_f32_e32 v118, s52, v38
	v_mul_f32_e32 v119, s53, v39
	v_add_f32_e32 v118, v118, v122
	v_add_f32_e32 v122, v119, v118
	v_mul_f32_e32 v118, s54, v42
	v_mul_f32_e32 v119, s55, v43
	v_add_f32_e32 v118, v118, v122
	v_add_f32_e32 v118, v119, v118
	v_mul_f32_e32 v114, s84, v32
	v_mul_f32_e32 v115, s85, v33
	v_add_f32_e32 v114, v114, v118
	v_add_f32_e32 v118, v115, v114
	v_mul_f32_e32 v114, s86, v44
	v_mul_f32_e32 v115, s87, v45
	s_load_dwordx8 s[92:99], s[30:31], 0x140
	s_load_dwordx4 s[52:55], s[30:31], 0x160
	s_load_dwordx4 s[84:87], s[30:31], 0x170
	v_mov_b32_e32 v116, v110
	v_add_f32_e32 v114, v114, v118
	v_add_f32_e32 v115, v115, v114
	v_cmp_ngt_f32_e32 vcc, v115, v110
	v_mov_b32_e32 v114, s21
	s_and_saveexec_b64 s[6:7], vcc
	s_cbranch_execz .LBB0_172
	v_cmp_ngt_f32_e32 vcc, v115, v111
	v_mov_b32_e32 v116, s21
	s_and_saveexec_b64 s[8:9], vcc
	s_cbranch_execz .LBB0_171
	v_cmp_gt_f32_e32 vcc, v115, v113
	s_and_saveexec_b64 s[18:19], vcc
	s_cbranch_execz .LBB0_170
	v_mov_b32_e32 v35, s21
	v_mov_b32_e32 v113, v115
	s_branch .LBB0_170
.LBB0_177:
	s_waitcnt lgkmcnt(0)
	s_or_b64 exec, exec, s[0:1]
	s_and_b32 s0, s20, 1
	s_or_b32 s0, s0, s34
	s_lshl_b32 s0, s0, 6
	v_lshlrev_b32_e32 v32, 8, v75
	v_or3_b32 v32, s0, v32, v189
	s_mov_b64 s[18:19], 0
	s_mov_b64 s[20:21], s[14:15]
	s_mov_b64 s[22:23], s[12:13]
	v_mov_b32_e32 v140, v114
	v_mov_b32_e32 v141, v34
	v_mov_b32_e32 v142, v35
	v_mov_b32_e32 v143, 0
	v_lshlrev_b32_e32 v147, 2, v189
	v_readfirstlane_b32 s73, v75
	s_mov_b32 s72, 0
